# GEMM k-loop: scalar-addressed LDS-DMA (saddr form, m0 stepped by SALU) interleaved with 2nd-half LDS reads; removes per-load VALU address math
# speedup vs baseline: 1.0205x; 1.0142x over previous
.LBB0_225:
	s_and_b32 s1, s0, 7
	s_mulk_i32 s1, 0xb4
	s_ashr_i32 s0, s0, 3
	s_add_i32 s1, s1, s0
	s_mul_hi_i32 s0, s1, 0x66666667
	s_lshr_b32 s3, s0, 31
	s_ashr_i32 s0, s0, 5
	s_add_i32 s0, s0, s3
	s_mul_i32 s3, s0, 0x50
	s_sub_i32 s1, s1, s3
	s_lshl_b32 s19, s0, 10
	s_lshl_b32 s0, s1, 7
	s_and_b32 s22, s0, 0x380
	s_lshl_b32 s3, s1, 4
	s_and_b32 s38, s3, 0xffffff80
	s_or_b32 s40, s19, s22
	s_ashr_i32 s39, s38, 31
	s_waitcnt vmcnt(0)
	s_ashr_i32 s41, s40, 31
	s_lshl_b64 s[0:1], s[38:39], 11
	s_lshl_b64 s[22:23], s[40:41], 11
	v_mov_b32_e32 v2, 0
	v_lshl_add_u64 v[66:67], v[98:99], 0, s[22:23]
	v_lshl_add_u64 v[68:69], v[100:101], 0, s[22:23]
	v_lshl_add_u64 v[70:71], v[102:103], 0, s[22:23]
	v_lshl_add_u64 v[72:73], v[104:105], 0, s[22:23]
	v_lshl_add_u64 v[74:75], v[106:107], 0, s[0:1]
	v_lshl_add_u64 v[76:77], v[108:109], 0, s[0:1]
	v_lshl_add_u64 v[78:79], v[110:111], 0, s[0:1]
	v_lshl_add_u64 v[80:81], v[112:113], 0, s[0:1]
	s_mov_b32 s19, 0
	v_mov_b32_e32 v3, v2
	v_mov_b32_e32 v4, v2
	v_mov_b32_e32 v5, v2
	v_mov_b32_e32 v6, v2
	v_mov_b32_e32 v7, v2
	v_mov_b32_e32 v8, v2
	v_mov_b32_e32 v9, v2
	v_mov_b32_e32 v10, v2
	v_mov_b32_e32 v11, v2
	v_mov_b32_e32 v12, v2
	v_mov_b32_e32 v13, v2
	v_mov_b32_e32 v14, v2
	v_mov_b32_e32 v15, v2
	v_mov_b32_e32 v16, v2
	v_mov_b32_e32 v17, v2
	v_mov_b32_e32 v18, v2
	v_mov_b32_e32 v19, v2
	v_mov_b32_e32 v20, v2
	v_mov_b32_e32 v21, v2
	v_mov_b32_e32 v22, v2
	v_mov_b32_e32 v23, v2
	v_mov_b32_e32 v24, v2
	v_mov_b32_e32 v25, v2
	v_mov_b32_e32 v26, v2
	v_mov_b32_e32 v27, v2
	v_mov_b32_e32 v28, v2
	v_mov_b32_e32 v29, v2
	v_mov_b32_e32 v30, v2
	v_mov_b32_e32 v31, v2
	v_mov_b32_e32 v32, v2
	v_mov_b32_e32 v33, v2
	v_mov_b32_e32 v34, v2
	v_mov_b32_e32 v35, v2
	v_mov_b32_e32 v36, v2
	v_mov_b32_e32 v37, v2
	v_mov_b32_e32 v38, v2
	v_mov_b32_e32 v39, v2
	v_mov_b32_e32 v40, v2
	v_mov_b32_e32 v41, v2
	v_mov_b32_e32 v42, v2
	v_mov_b32_e32 v43, v2
	v_mov_b32_e32 v44, v2
	v_mov_b32_e32 v45, v2
	v_mov_b32_e32 v46, v2
	v_mov_b32_e32 v47, v2
	v_mov_b32_e32 v48, v2
	v_mov_b32_e32 v49, v2
	v_mov_b32_e32 v50, v2
	v_mov_b32_e32 v51, v2
	v_mov_b32_e32 v52, v2
	v_mov_b32_e32 v53, v2
	v_mov_b32_e32 v54, v2
	v_mov_b32_e32 v55, v2
	v_mov_b32_e32 v56, v2
	v_mov_b32_e32 v57, v2
	v_mov_b32_e32 v58, v2
	v_mov_b32_e32 v59, v2
	v_mov_b32_e32 v60, v2
	v_mov_b32_e32 v61, v2
	v_mov_b32_e32 v62, v2
	v_mov_b32_e32 v63, v2
	v_mov_b32_e32 v64, v2
	v_mov_b32_e32 v65, v2
	v_and_b32_e32 v214, 63, v188
	v_lshrrev_b32_e32 v215, 3, v214
	v_and_b32_e32 v216, 7, v214
	v_xor_b32_e32 v216, v216, v215
	v_mul_u32_u24_e32 v246, 0x800, v215
	v_lshl_add_u32 v246, v216, 4, v246
	v_add_u32_e32 v247, 0x4000, v246
	v_add_u32_e32 v248, 0x8000, v246
	v_add_u32_e32 v249, 0xc000, v246
	v_lshrrev_b32_e32 v250, 6, v188
	v_lshlrev_b32_e32 v250, 12, v250
	v_readfirstlane_b32 s98, v66
	v_readfirstlane_b32 s99, v67
	v_readfirstlane_b32 s100, v74
	v_readfirstlane_b32 s101, v75
	s_add_u32 s98, s98, s44
	s_addc_u32 s99, s99, s45
	s_add_u32 s100, s100, s44
	s_addc_u32 s101, s101, s45
	s_waitcnt vmcnt(0) lgkmcnt(0)
	s_barrier
.LBB0_226:
	s_and_b32 s0, s19, 0x2000
	s_xor_b32 s1, s0, 0x2000
	s_lshl_b32 s0, s0, 1
	v_add_u32_e32 v0, s0, v151
	v_add_u32_e32 v159, s0, v152
	v_add_u32_e32 v126, v0, v157
	v_add_u32_e32 v164, v159, v157
	ds_read_b128 v[82:85], v126
	ds_read_b128 v[86:89], v126 offset:2048
	ds_read_b128 v[122:125], v126 offset:4096
	ds_read_b128 v[126:129], v126 offset:6144
	ds_read_b128 v[130:133], v164 offset:32768
	ds_read_b128 v[134:137], v164 offset:34816
	ds_read_b128 v[160:163], v164 offset:36864
	ds_read_b128 v[164:167], v164 offset:38912
	s_lshl_b32 s1, s1, 1
	v_readfirstlane_b32 s0, v250
	v_add_u32_e32 v0, v0, v158
	s_add_u32 m0, s0, s1
	ds_read_b128 v[214:217], v0
	global_load_lds_dwordx4 v246, s[98:99]
	s_add_u32 m0, m0, 0x8000
	ds_read_b128 v[218:221], v0 offset:2048
	global_load_lds_dwordx4 v246, s[100:101]
	s_add_u32 m0, m0, 0xffff8400
	ds_read_b128 v[222:225], v0 offset:4096
	global_load_lds_dwordx4 v247, s[98:99]
	s_add_u32 m0, m0, 0x8000
	ds_read_b128 v[226:229], v0 offset:6144
	global_load_lds_dwordx4 v247, s[100:101]
	s_add_u32 m0, m0, 0xffff8400
	v_add_u32_e32 v0, v159, v158
	ds_read_b128 v[230:233], v0 offset:32768
	global_load_lds_dwordx4 v248, s[98:99]
	s_add_u32 m0, m0, 0x8000
	ds_read_b128 v[234:237], v0 offset:34816
	global_load_lds_dwordx4 v248, s[100:101]
	s_add_u32 m0, m0, 0xffff8400
	ds_read_b128 v[238:241], v0 offset:36864
	global_load_lds_dwordx4 v249, s[98:99]
	s_add_u32 m0, m0, 0x8000
	s_setprio 1
	s_waitcnt lgkmcnt(7)
	ds_read_b128 v[242:245], v0 offset:38912
	global_load_lds_dwordx4 v249, s[100:101]
	s_add_u32 s98, s98, 0x80
	s_addc_u32 s99, s99, 0
	s_add_u32 s100, s100, 0x80
	s_addc_u32 s101, s101, 0
	v_mfma_f32_16x16x32_bf16 v[2:5], v[130:133], v[82:85], v[2:5]
	v_mfma_f32_16x16x32_bf16 v[6:9], v[134:137], v[82:85], v[6:9]
	v_mfma_f32_16x16x32_bf16 v[10:13], v[160:163], v[82:85], v[10:13]
	v_mfma_f32_16x16x32_bf16 v[14:17], v[164:167], v[82:85], v[14:17]
	v_mfma_f32_16x16x32_bf16 v[18:21], v[130:133], v[86:89], v[18:21]
	v_mfma_f32_16x16x32_bf16 v[22:25], v[134:137], v[86:89], v[22:25]
	v_mfma_f32_16x16x32_bf16 v[26:29], v[160:163], v[86:89], v[26:29]
	v_mfma_f32_16x16x32_bf16 v[30:33], v[164:167], v[86:89], v[30:33]
	v_mfma_f32_16x16x32_bf16 v[34:37], v[130:133], v[122:125], v[34:37]
	v_mfma_f32_16x16x32_bf16 v[38:41], v[134:137], v[122:125], v[38:41]
	v_mfma_f32_16x16x32_bf16 v[42:45], v[160:163], v[122:125], v[42:45]
	v_mfma_f32_16x16x32_bf16 v[46:49], v[164:167], v[122:125], v[46:49]
	v_mfma_f32_16x16x32_bf16 v[50:53], v[130:133], v[126:129], v[50:53]
	v_mfma_f32_16x16x32_bf16 v[54:57], v[134:137], v[126:129], v[54:57]
	v_mfma_f32_16x16x32_bf16 v[58:61], v[160:163], v[126:129], v[58:61]
	v_mfma_f32_16x16x32_bf16 v[62:65], v[164:167], v[126:129], v[62:65]
	s_waitcnt lgkmcnt(0)
	v_mfma_f32_16x16x32_bf16 v[2:5], v[230:233], v[214:217], v[2:5]
	v_mfma_f32_16x16x32_bf16 v[6:9], v[234:237], v[214:217], v[6:9]
	v_mfma_f32_16x16x32_bf16 v[10:13], v[238:241], v[214:217], v[10:13]
	v_mfma_f32_16x16x32_bf16 v[14:17], v[242:245], v[214:217], v[14:17]
	v_mfma_f32_16x16x32_bf16 v[18:21], v[230:233], v[218:221], v[18:21]
	v_mfma_f32_16x16x32_bf16 v[22:25], v[234:237], v[218:221], v[22:25]
	v_mfma_f32_16x16x32_bf16 v[26:29], v[238:241], v[218:221], v[26:29]
	v_mfma_f32_16x16x32_bf16 v[30:33], v[242:245], v[218:221], v[30:33]
	v_mfma_f32_16x16x32_bf16 v[34:37], v[230:233], v[222:225], v[34:37]
	v_mfma_f32_16x16x32_bf16 v[38:41], v[234:237], v[222:225], v[38:41]
	v_mfma_f32_16x16x32_bf16 v[42:45], v[238:241], v[222:225], v[42:45]
	v_mfma_f32_16x16x32_bf16 v[46:49], v[242:245], v[222:225], v[46:49]
	v_mfma_f32_16x16x32_bf16 v[50:53], v[230:233], v[226:229], v[50:53]
	v_mfma_f32_16x16x32_bf16 v[54:57], v[234:237], v[226:229], v[54:57]
	v_mfma_f32_16x16x32_bf16 v[58:61], v[238:241], v[226:229], v[58:61]
	v_mfma_f32_16x16x32_bf16 v[62:65], v[242:245], v[226:229], v[62:65]
	s_setprio 0
	s_addk_i32 s19, 0x2000
	s_waitcnt vmcnt(0)
	s_add_u32 s44, s44, 0x80
	s_addc_u32 s45, s45, 0
	s_cmpk_eq_i32 s44, 0x780
	s_waitcnt vmcnt(0)
	s_barrier
	s_cbranch_scc0 .LBB0_226
	s_andn2_b64 vcc, exec, s[42:43]
	s_cbranch_vccnz .LBB0_229
	v_lshl_add_u64 v[66:67], v[90:91], 0, s[46:47]
	v_readfirstlane_b32 s0, v138
	v_lshl_add_u64 v[68:69], v[66:67], 0, v[114:115]
	v_lshl_add_u64 v[74:75], v[92:93], 0, s[52:53]
	s_mov_b32 m0, s0
	v_readfirstlane_b32 s0, v139
	v_lshl_add_u64 v[76:77], v[74:75], 0, v[120:121]
	v_lshl_add_u64 v[78:79], v[74:75], 0, v[118:119]
	v_lshl_add_u64 v[80:81], v[74:75], 0, v[116:117]
	v_lshl_add_u64 v[74:75], v[74:75], 0, v[114:115]
	global_load_lds_dwordx4 v[68:69], off
	s_mov_b32 m0, s0
	v_readfirstlane_b32 s0, v140
	v_lshl_add_u64 v[70:71], v[66:67], 0, v[116:117]
	global_load_lds_dwordx4 v[74:75], off
	s_mov_b32 m0, s0
	v_readfirstlane_b32 s0, v141
	global_load_lds_dwordx4 v[70:71], off
	s_mov_b32 m0, s0
	v_readfirstlane_b32 s0, v142
	v_lshl_add_u64 v[72:73], v[66:67], 0, v[118:119]
	global_load_lds_dwordx4 v[80:81], off
	s_mov_b32 m0, s0
	v_readfirstlane_b32 s0, v143
	global_load_lds_dwordx4 v[72:73], off
	s_mov_b32 m0, s0
	v_readfirstlane_b32 s0, v144
	v_lshl_add_u64 v[66:67], v[66:67], 0, v[120:121]
	global_load_lds_dwordx4 v[78:79], off
	s_mov_b32 m0, s0
	v_readfirstlane_b32 s0, v145
	global_load_lds_dwordx4 v[66:67], off
	s_mov_b32 m0, s0
	s_nop 0
	global_load_lds_dwordx4 v[76:77], off

.LBB0_891:
	s_and_b32 s1, s0, 7
	s_mul_i32 s1, s1, s2
	s_ashr_i32 s0, s0, 3
	s_add_i32 s0, s1, s0
	s_ashr_i32 s1, s0, 31
	s_lshr_b32 s1, s1, 26
	s_add_i32 s1, s0, s1
	s_and_b32 s19, s1, 0xffffffc0
	s_sub_i32 s0, s0, s19
	s_lshl_b32 s1, s1, 4
	s_and_b32 s19, s1, 0xfffffc00
	s_lshl_b32 s1, s0, 7
	s_and_b32 s26, s1, 0x380
	s_lshl_b32 s0, s0, 4
	s_and_b32 s42, s0, 0xffffff80
	s_or_b32 s40, s19, s26
	s_ashr_i32 s43, s42, 31
	s_waitcnt vmcnt(0)
	s_ashr_i32 s41, s40, 31
	s_lshl_b64 s[0:1], s[42:43], 11
	s_lshl_b64 s[26:27], s[40:41], 11
	v_mov_b32_e32 v2, 0
	v_lshl_add_u64 v[96:97], v[70:71], 0, s[26:27]
	v_lshl_add_u64 v[98:99], v[72:73], 0, s[26:27]
	v_lshl_add_u64 v[100:101], v[74:75], 0, s[26:27]
	v_lshl_add_u64 v[102:103], v[76:77], 0, s[26:27]
	v_lshl_add_u64 v[104:105], v[78:79], 0, s[0:1]
	v_lshl_add_u64 v[106:107], v[80:81], 0, s[0:1]
	v_lshl_add_u64 v[108:109], v[82:83], 0, s[0:1]
	v_lshl_add_u64 v[110:111], v[84:85], 0, s[0:1]
	s_mov_b32 s19, 0
	v_mov_b32_e32 v3, v2
	v_mov_b32_e32 v4, v2
	v_mov_b32_e32 v5, v2
	v_mov_b32_e32 v6, v2
	v_mov_b32_e32 v7, v2
	v_mov_b32_e32 v8, v2
	v_mov_b32_e32 v9, v2
	v_mov_b32_e32 v10, v2
	v_mov_b32_e32 v11, v2
	v_mov_b32_e32 v12, v2
	v_mov_b32_e32 v13, v2
	v_mov_b32_e32 v14, v2
	v_mov_b32_e32 v15, v2
	v_mov_b32_e32 v16, v2
	v_mov_b32_e32 v17, v2
	v_mov_b32_e32 v18, v2
	v_mov_b32_e32 v19, v2
	v_mov_b32_e32 v20, v2
	v_mov_b32_e32 v21, v2
	v_mov_b32_e32 v22, v2
	v_mov_b32_e32 v23, v2
	v_mov_b32_e32 v24, v2
	v_mov_b32_e32 v25, v2
	v_mov_b32_e32 v26, v2
	v_mov_b32_e32 v27, v2
	v_mov_b32_e32 v28, v2
	v_mov_b32_e32 v29, v2
	v_mov_b32_e32 v30, v2
	v_mov_b32_e32 v31, v2
	v_mov_b32_e32 v32, v2
	v_mov_b32_e32 v33, v2
	v_mov_b32_e32 v34, v2
	v_mov_b32_e32 v35, v2
	v_mov_b32_e32 v36, v2
	v_mov_b32_e32 v37, v2
	v_mov_b32_e32 v38, v2
	v_mov_b32_e32 v39, v2
	v_mov_b32_e32 v40, v2
	v_mov_b32_e32 v41, v2
	v_mov_b32_e32 v42, v2
	v_mov_b32_e32 v43, v2
	v_mov_b32_e32 v44, v2
	v_mov_b32_e32 v45, v2
	v_mov_b32_e32 v46, v2
	v_mov_b32_e32 v47, v2
	v_mov_b32_e32 v48, v2
	v_mov_b32_e32 v49, v2
	v_mov_b32_e32 v50, v2
	v_mov_b32_e32 v51, v2
	v_mov_b32_e32 v52, v2
	v_mov_b32_e32 v53, v2
	v_mov_b32_e32 v54, v2
	v_mov_b32_e32 v55, v2
	v_mov_b32_e32 v56, v2
	v_mov_b32_e32 v57, v2
	v_mov_b32_e32 v58, v2
	v_mov_b32_e32 v59, v2
	v_mov_b32_e32 v60, v2
	v_mov_b32_e32 v61, v2
	v_mov_b32_e32 v62, v2
	v_mov_b32_e32 v63, v2
	v_mov_b32_e32 v64, v2
	v_mov_b32_e32 v65, v2
	v_and_b32_e32 v214, 63, v188
	v_lshrrev_b32_e32 v215, 3, v214
	v_and_b32_e32 v216, 7, v214
	v_xor_b32_e32 v216, v216, v215
	v_mul_u32_u24_e32 v246, 0x800, v215
	v_lshl_add_u32 v246, v216, 4, v246
	v_add_u32_e32 v247, 0x4000, v246
	v_add_u32_e32 v248, 0x8000, v246
	v_add_u32_e32 v249, 0xc000, v246
	v_lshrrev_b32_e32 v250, 6, v188
	v_lshlrev_b32_e32 v250, 12, v250
	v_readfirstlane_b32 s98, v96
	v_readfirstlane_b32 s99, v97
	v_readfirstlane_b32 s100, v104
	v_readfirstlane_b32 s101, v105
	s_add_u32 s98, s98, s46
	s_addc_u32 s99, s99, s47
	s_add_u32 s100, s100, s46
	s_addc_u32 s101, s101, s47
	s_waitcnt lgkmcnt(0)
	s_barrier
.LBB0_892:
	s_and_b32 s0, s19, 0x2000
	s_xor_b32 s1, s0, 0x2000
	s_lshl_b32 s0, s0, 1
	v_add_u32_e32 v95, s0, v125
	v_add_u32_e32 v162, s0, v126
	v_add_u32_e32 v142, v95, v128
	v_add_u32_e32 v158, v162, v128
	ds_read_b128 v[130:133], v142
	ds_read_b128 v[134:137], v142 offset:2048
	ds_read_b128 v[138:141], v142 offset:4096
	ds_read_b128 v[142:145], v142 offset:6144
	ds_read_b128 v[146:149], v158 offset:32768
	ds_read_b128 v[150:153], v158 offset:34816
	ds_read_b128 v[154:157], v158 offset:36864
	ds_read_b128 v[158:161], v158 offset:38912
	s_lshl_b32 s1, s1, 1
	v_readfirstlane_b32 s0, v250
	v_add_u32_e32 v95, v95, v129
	s_add_u32 m0, s0, s1
	ds_read_b128 v[214:217], v95
	global_load_lds_dwordx4 v246, s[98:99]
	s_add_u32 m0, m0, 0x8000
	ds_read_b128 v[218:221], v95 offset:2048
	global_load_lds_dwordx4 v246, s[100:101]
	s_add_u32 m0, m0, 0xffff8400
	ds_read_b128 v[222:225], v95 offset:4096
	global_load_lds_dwordx4 v247, s[98:99]
	s_add_u32 m0, m0, 0x8000
	ds_read_b128 v[226:229], v95 offset:6144
	global_load_lds_dwordx4 v247, s[100:101]
	s_add_u32 m0, m0, 0xffff8400
	v_add_u32_e32 v95, v162, v129
	ds_read_b128 v[230:233], v95 offset:32768
	global_load_lds_dwordx4 v248, s[98:99]
	s_add_u32 m0, m0, 0x8000
	ds_read_b128 v[234:237], v95 offset:34816
	global_load_lds_dwordx4 v248, s[100:101]
	s_add_u32 m0, m0, 0xffff8400
	ds_read_b128 v[238:241], v95 offset:36864
	global_load_lds_dwordx4 v249, s[98:99]
	s_add_u32 m0, m0, 0x8000
	s_setprio 1
	s_waitcnt lgkmcnt(7)
	ds_read_b128 v[242:245], v95 offset:38912
	global_load_lds_dwordx4 v249, s[100:101]
	s_add_u32 s98, s98, 0x80
	s_addc_u32 s99, s99, 0
	s_add_u32 s100, s100, 0x80
	s_addc_u32 s101, s101, 0
	v_mfma_f32_16x16x32_bf16 v[2:5], v[146:149], v[130:133], v[2:5]
	v_mfma_f32_16x16x32_bf16 v[6:9], v[150:153], v[130:133], v[6:9]
	v_mfma_f32_16x16x32_bf16 v[10:13], v[154:157], v[130:133], v[10:13]
	v_mfma_f32_16x16x32_bf16 v[14:17], v[158:161], v[130:133], v[14:17]
	v_mfma_f32_16x16x32_bf16 v[18:21], v[146:149], v[134:137], v[18:21]
	v_mfma_f32_16x16x32_bf16 v[22:25], v[150:153], v[134:137], v[22:25]
	v_mfma_f32_16x16x32_bf16 v[26:29], v[154:157], v[134:137], v[26:29]
	v_mfma_f32_16x16x32_bf16 v[30:33], v[158:161], v[134:137], v[30:33]
	v_mfma_f32_16x16x32_bf16 v[34:37], v[146:149], v[138:141], v[34:37]
	v_mfma_f32_16x16x32_bf16 v[38:41], v[150:153], v[138:141], v[38:41]
	v_mfma_f32_16x16x32_bf16 v[42:45], v[154:157], v[138:141], v[42:45]
	v_mfma_f32_16x16x32_bf16 v[46:49], v[158:161], v[138:141], v[46:49]
	v_mfma_f32_16x16x32_bf16 v[50:53], v[146:149], v[142:145], v[50:53]
	v_mfma_f32_16x16x32_bf16 v[54:57], v[150:153], v[142:145], v[54:57]
	v_mfma_f32_16x16x32_bf16 v[58:61], v[154:157], v[142:145], v[58:61]
	v_mfma_f32_16x16x32_bf16 v[62:65], v[158:161], v[142:145], v[62:65]
	s_waitcnt lgkmcnt(0)
	v_mfma_f32_16x16x32_bf16 v[2:5], v[230:233], v[214:217], v[2:5]
	v_mfma_f32_16x16x32_bf16 v[6:9], v[234:237], v[214:217], v[6:9]
	v_mfma_f32_16x16x32_bf16 v[10:13], v[238:241], v[214:217], v[10:13]
	v_mfma_f32_16x16x32_bf16 v[14:17], v[242:245], v[214:217], v[14:17]
	v_mfma_f32_16x16x32_bf16 v[18:21], v[230:233], v[218:221], v[18:21]
	v_mfma_f32_16x16x32_bf16 v[22:25], v[234:237], v[218:221], v[22:25]
	v_mfma_f32_16x16x32_bf16 v[26:29], v[238:241], v[218:221], v[26:29]
	v_mfma_f32_16x16x32_bf16 v[30:33], v[242:245], v[218:221], v[30:33]
	v_mfma_f32_16x16x32_bf16 v[34:37], v[230:233], v[222:225], v[34:37]
	v_mfma_f32_16x16x32_bf16 v[38:41], v[234:237], v[222:225], v[38:41]
	v_mfma_f32_16x16x32_bf16 v[42:45], v[238:241], v[222:225], v[42:45]
	v_mfma_f32_16x16x32_bf16 v[46:49], v[242:245], v[222:225], v[46:49]
	v_mfma_f32_16x16x32_bf16 v[50:53], v[230:233], v[226:229], v[50:53]
	v_mfma_f32_16x16x32_bf16 v[54:57], v[234:237], v[226:229], v[54:57]
	v_mfma_f32_16x16x32_bf16 v[58:61], v[238:241], v[226:229], v[58:61]
	v_mfma_f32_16x16x32_bf16 v[62:65], v[242:245], v[226:229], v[62:65]
	s_setprio 0
	s_waitcnt vmcnt(0)
	s_add_u32 s46, s46, 0x80
	s_addc_u32 s47, s47, 0
	s_addk_i32 s19, 0x2000
	s_cmpk_eq_i32 s46, 0x780
	s_waitcnt vmcnt(0)
	s_barrier
	s_cbranch_scc0 .LBB0_892
	s_andn2_b64 vcc, exec, s[44:45]
	s_cbranch_vccnz .LBB0_888
	v_lshl_add_u64 v[96:97], s[56:57], 1, v[66:67]
	v_readfirstlane_b32 s0, v113
	v_lshl_add_u64 v[98:99], v[96:97], 0, v[86:87]
	v_lshl_add_u64 v[104:105], s[52:53], 1, v[68:69]
	s_mov_b32 m0, s0
	v_readfirstlane_b32 s0, v114
	v_lshl_add_u64 v[106:107], v[104:105], 0, v[92:93]
	v_lshl_add_u64 v[108:109], v[104:105], 0, v[90:91]
	v_lshl_add_u64 v[110:111], v[104:105], 0, v[88:89]
	v_lshl_add_u64 v[104:105], v[104:105], 0, v[86:87]
	global_load_lds_dwordx4 v[98:99], off
	s_mov_b32 m0, s0
	v_readfirstlane_b32 s0, v115
	v_lshl_add_u64 v[100:101], v[96:97], 0, v[88:89]
	global_load_lds_dwordx4 v[104:105], off
	s_mov_b32 m0, s0
	v_readfirstlane_b32 s0, v116
	global_load_lds_dwordx4 v[100:101], off
	s_mov_b32 m0, s0
	v_readfirstlane_b32 s0, v117
	v_lshl_add_u64 v[102:103], v[96:97], 0, v[90:91]
	global_load_lds_dwordx4 v[110:111], off
	s_mov_b32 m0, s0
	v_readfirstlane_b32 s0, v118
	global_load_lds_dwordx4 v[102:103], off
	s_mov_b32 m0, s0
	v_readfirstlane_b32 s0, v119
	v_lshl_add_u64 v[96:97], v[96:97], 0, v[92:93]
	global_load_lds_dwordx4 v[108:109], off
	s_mov_b32 m0, s0
	v_readfirstlane_b32 s0, v120
	global_load_lds_dwordx4 v[96:97], off
	s_mov_b32 m0, s0
	s_nop 0
	global_load_lds_dwordx4 v[106:107], off
	s_branch .LBB0_888

.LBB0_999:
	s_and_b32 s1, s0, 7
	s_mul_i32 s1, s1, s3
	s_ashr_i32 s0, s0, 3
	s_add_i32 s1, s1, s0
	s_mul_hi_i32 s0, s1, 0x2e8ba2e9
	s_lshr_b32 s26, s0, 31
	s_ashr_i32 s0, s0, 6
	s_add_i32 s0, s0, s26
	s_mul_i32 s26, s0, 0x160
	s_sub_i32 s1, s1, s26
	s_lshl_b32 s26, s0, 10
	s_lshl_b32 s0, s1, 7
	s_and_b32 s27, s0, 0x380
	s_lshl_b32 s0, s1, 4
	s_and_b32 s40, s0, 0xffffff80
	s_or_b32 s42, s26, s27
	s_ashr_i32 s41, s40, 31
	s_waitcnt vmcnt(0)
	s_ashr_i32 s43, s42, 31
	s_lshl_b64 s[0:1], s[40:41], 11
	s_lshl_b64 s[26:27], s[42:43], 11
	v_mov_b32_e32 v2, 0
	v_lshl_add_u64 v[94:95], v[70:71], 0, s[26:27]
	v_lshl_add_u64 v[96:97], v[72:73], 0, s[26:27]
	v_lshl_add_u64 v[98:99], v[74:75], 0, s[26:27]
	v_lshl_add_u64 v[100:101], v[76:77], 0, s[26:27]
	v_lshl_add_u64 v[102:103], v[78:79], 0, s[0:1]
	v_lshl_add_u64 v[104:105], v[80:81], 0, s[0:1]
	v_lshl_add_u64 v[106:107], v[82:83], 0, s[0:1]
	v_lshl_add_u64 v[108:109], v[84:85], 0, s[0:1]
	s_mov_b32 s33, 0
	v_mov_b32_e32 v3, v2
	v_mov_b32_e32 v4, v2
	v_mov_b32_e32 v5, v2
	v_mov_b32_e32 v6, v2
	v_mov_b32_e32 v7, v2
	v_mov_b32_e32 v8, v2
	v_mov_b32_e32 v9, v2
	v_mov_b32_e32 v10, v2
	v_mov_b32_e32 v11, v2
	v_mov_b32_e32 v12, v2
	v_mov_b32_e32 v13, v2
	v_mov_b32_e32 v14, v2
	v_mov_b32_e32 v15, v2
	v_mov_b32_e32 v16, v2
	v_mov_b32_e32 v17, v2
	v_mov_b32_e32 v18, v2
	v_mov_b32_e32 v19, v2
	v_mov_b32_e32 v20, v2
	v_mov_b32_e32 v21, v2
	v_mov_b32_e32 v22, v2
	v_mov_b32_e32 v23, v2
	v_mov_b32_e32 v24, v2
	v_mov_b32_e32 v25, v2
	v_mov_b32_e32 v26, v2
	v_mov_b32_e32 v27, v2
	v_mov_b32_e32 v28, v2
	v_mov_b32_e32 v29, v2
	v_mov_b32_e32 v30, v2
	v_mov_b32_e32 v31, v2
	v_mov_b32_e32 v32, v2
	v_mov_b32_e32 v33, v2
	v_mov_b32_e32 v34, v2
	v_mov_b32_e32 v35, v2
	v_mov_b32_e32 v36, v2
	v_mov_b32_e32 v37, v2
	v_mov_b32_e32 v38, v2
	v_mov_b32_e32 v39, v2
	v_mov_b32_e32 v40, v2
	v_mov_b32_e32 v41, v2
	v_mov_b32_e32 v42, v2
	v_mov_b32_e32 v43, v2
	v_mov_b32_e32 v44, v2
	v_mov_b32_e32 v45, v2
	v_mov_b32_e32 v46, v2
	v_mov_b32_e32 v47, v2
	v_mov_b32_e32 v48, v2
	v_mov_b32_e32 v49, v2
	v_mov_b32_e32 v50, v2
	v_mov_b32_e32 v51, v2
	v_mov_b32_e32 v52, v2
	v_mov_b32_e32 v53, v2
	v_mov_b32_e32 v54, v2
	v_mov_b32_e32 v55, v2
	v_mov_b32_e32 v56, v2
	v_mov_b32_e32 v57, v2
	v_mov_b32_e32 v58, v2
	v_mov_b32_e32 v59, v2
	v_mov_b32_e32 v60, v2
	v_mov_b32_e32 v61, v2
	v_mov_b32_e32 v62, v2
	v_mov_b32_e32 v63, v2
	v_mov_b32_e32 v64, v2
	v_mov_b32_e32 v65, v2
	v_and_b32_e32 v214, 63, v188
	v_lshrrev_b32_e32 v215, 3, v214
	v_and_b32_e32 v216, 7, v214
	v_xor_b32_e32 v216, v216, v215
	v_mul_u32_u24_e32 v246, 0x800, v215
	v_lshl_add_u32 v246, v216, 4, v246
	v_add_u32_e32 v247, 0x4000, v246
	v_add_u32_e32 v248, 0x8000, v246
	v_add_u32_e32 v249, 0xc000, v246
	v_lshrrev_b32_e32 v250, 6, v188
	v_lshlrev_b32_e32 v250, 12, v250
	v_readfirstlane_b32 s98, v94
	v_readfirstlane_b32 s99, v95
	v_readfirstlane_b32 s100, v102
	v_readfirstlane_b32 s101, v103
	s_add_u32 s98, s98, s46
	s_addc_u32 s99, s99, s47
	s_add_u32 s100, s100, s46
	s_addc_u32 s101, s101, s47
	s_waitcnt lgkmcnt(0)
	s_barrier
.LBB0_1000:
	s_and_b32 s0, s33, 0x2000
	s_xor_b32 s1, s0, 0x2000
	s_lshl_b32 s0, s0, 1
	v_add_u32_e32 v0, s0, v123
	v_add_u32_e32 v129, s0, v124
	v_add_u32_e32 v142, v0, v127
	v_add_u32_e32 v158, v129, v127
	ds_read_b128 v[130:133], v142
	ds_read_b128 v[134:137], v142 offset:2048
	ds_read_b128 v[138:141], v142 offset:4096
	ds_read_b128 v[142:145], v142 offset:6144
	ds_read_b128 v[146:149], v158 offset:32768
	ds_read_b128 v[150:153], v158 offset:34816
	ds_read_b128 v[154:157], v158 offset:36864
	ds_read_b128 v[158:161], v158 offset:38912
	s_lshl_b32 s1, s1, 1
	v_readfirstlane_b32 s0, v250
	v_add_u32_e32 v0, v0, v128
	s_add_u32 m0, s0, s1
	ds_read_b128 v[214:217], v0
	global_load_lds_dwordx4 v246, s[98:99]
	s_add_u32 m0, m0, 0x8000
	ds_read_b128 v[218:221], v0 offset:2048
	global_load_lds_dwordx4 v246, s[100:101]
	s_add_u32 m0, m0, 0xffff8400
	ds_read_b128 v[222:225], v0 offset:4096
	global_load_lds_dwordx4 v247, s[98:99]
	s_add_u32 m0, m0, 0x8000
	ds_read_b128 v[226:229], v0 offset:6144
	global_load_lds_dwordx4 v247, s[100:101]
	s_add_u32 m0, m0, 0xffff8400
	v_add_u32_e32 v0, v129, v128
	ds_read_b128 v[230:233], v0 offset:32768
	global_load_lds_dwordx4 v248, s[98:99]
	s_add_u32 m0, m0, 0x8000
	ds_read_b128 v[234:237], v0 offset:34816
	global_load_lds_dwordx4 v248, s[100:101]
	s_add_u32 m0, m0, 0xffff8400
	ds_read_b128 v[238:241], v0 offset:36864
	global_load_lds_dwordx4 v249, s[98:99]
	s_add_u32 m0, m0, 0x8000
	s_setprio 1
	s_waitcnt lgkmcnt(7)
	ds_read_b128 v[242:245], v0 offset:38912
	global_load_lds_dwordx4 v249, s[100:101]
	s_add_u32 s98, s98, 0x80
	s_addc_u32 s99, s99, 0
	s_add_u32 s100, s100, 0x80
	s_addc_u32 s101, s101, 0
	v_mfma_f32_16x16x32_bf16 v[62:65], v[146:149], v[130:133], v[62:65]
	v_mfma_f32_16x16x32_bf16 v[58:61], v[150:153], v[130:133], v[58:61]
	v_mfma_f32_16x16x32_bf16 v[54:57], v[154:157], v[130:133], v[54:57]
	v_mfma_f32_16x16x32_bf16 v[50:53], v[158:161], v[130:133], v[50:53]
	v_mfma_f32_16x16x32_bf16 v[46:49], v[146:149], v[134:137], v[46:49]
	v_mfma_f32_16x16x32_bf16 v[42:45], v[150:153], v[134:137], v[42:45]
	v_mfma_f32_16x16x32_bf16 v[38:41], v[154:157], v[134:137], v[38:41]
	v_mfma_f32_16x16x32_bf16 v[34:37], v[158:161], v[134:137], v[34:37]
	v_mfma_f32_16x16x32_bf16 v[30:33], v[146:149], v[138:141], v[30:33]
	v_mfma_f32_16x16x32_bf16 v[26:29], v[150:153], v[138:141], v[26:29]
	v_mfma_f32_16x16x32_bf16 v[22:25], v[154:157], v[138:141], v[22:25]
	v_mfma_f32_16x16x32_bf16 v[18:21], v[158:161], v[138:141], v[18:21]
	v_mfma_f32_16x16x32_bf16 v[14:17], v[146:149], v[142:145], v[14:17]
	v_mfma_f32_16x16x32_bf16 v[10:13], v[150:153], v[142:145], v[10:13]
	v_mfma_f32_16x16x32_bf16 v[6:9], v[154:157], v[142:145], v[6:9]
	v_mfma_f32_16x16x32_bf16 v[2:5], v[158:161], v[142:145], v[2:5]
	s_waitcnt lgkmcnt(0)
	v_mfma_f32_16x16x32_bf16 v[62:65], v[230:233], v[214:217], v[62:65]
	v_mfma_f32_16x16x32_bf16 v[58:61], v[234:237], v[214:217], v[58:61]
	v_mfma_f32_16x16x32_bf16 v[54:57], v[238:241], v[214:217], v[54:57]
	v_mfma_f32_16x16x32_bf16 v[50:53], v[242:245], v[214:217], v[50:53]
	v_mfma_f32_16x16x32_bf16 v[46:49], v[230:233], v[218:221], v[46:49]
	v_mfma_f32_16x16x32_bf16 v[42:45], v[234:237], v[218:221], v[42:45]
	v_mfma_f32_16x16x32_bf16 v[38:41], v[238:241], v[218:221], v[38:41]
	v_mfma_f32_16x16x32_bf16 v[34:37], v[242:245], v[218:221], v[34:37]
	v_mfma_f32_16x16x32_bf16 v[30:33], v[230:233], v[222:225], v[30:33]
	v_mfma_f32_16x16x32_bf16 v[26:29], v[234:237], v[222:225], v[26:29]
	v_mfma_f32_16x16x32_bf16 v[22:25], v[238:241], v[222:225], v[22:25]
	v_mfma_f32_16x16x32_bf16 v[18:21], v[242:245], v[222:225], v[18:21]
	v_mfma_f32_16x16x32_bf16 v[14:17], v[230:233], v[226:229], v[14:17]
	v_mfma_f32_16x16x32_bf16 v[10:13], v[234:237], v[226:229], v[10:13]
	v_mfma_f32_16x16x32_bf16 v[6:9], v[238:241], v[226:229], v[6:9]
	v_mfma_f32_16x16x32_bf16 v[2:5], v[242:245], v[226:229], v[2:5]
	s_setprio 0
	s_addk_i32 s33, 0x2000
	s_waitcnt vmcnt(0)
	s_add_u32 s46, s46, 0x80
	s_addc_u32 s47, s47, 0
	s_cmpk_eq_i32 s46, 0x780
	s_waitcnt vmcnt(0)
	s_barrier
	s_cbranch_scc0 .LBB0_1000
	s_andn2_b64 vcc, exec, s[44:45]
	s_cbranch_vccnz .LBB0_996
	v_lshl_add_u64 v[94:95], v[66:67], 0, s[52:53]
	v_readfirstlane_b32 s0, v111
	v_lshl_add_u64 v[96:97], v[94:95], 0, v[86:87]
	v_lshl_add_u64 v[102:103], v[68:69], 0, s[56:57]
	s_mov_b32 m0, s0
	v_readfirstlane_b32 s0, v112
	v_lshl_add_u64 v[104:105], v[102:103], 0, v[92:93]
	v_lshl_add_u64 v[106:107], v[102:103], 0, v[90:91]
	v_lshl_add_u64 v[108:109], v[102:103], 0, v[88:89]
	v_lshl_add_u64 v[102:103], v[102:103], 0, v[86:87]
	global_load_lds_dwordx4 v[96:97], off
	s_mov_b32 m0, s0
	v_readfirstlane_b32 s0, v113
	v_lshl_add_u64 v[98:99], v[94:95], 0, v[88:89]
	global_load_lds_dwordx4 v[102:103], off
	s_mov_b32 m0, s0
	v_readfirstlane_b32 s0, v114
	global_load_lds_dwordx4 v[98:99], off
	s_mov_b32 m0, s0
	v_readfirstlane_b32 s0, v115
	v_lshl_add_u64 v[100:101], v[94:95], 0, v[90:91]
	global_load_lds_dwordx4 v[108:109], off
	s_mov_b32 m0, s0
	v_readfirstlane_b32 s0, v116
	global_load_lds_dwordx4 v[100:101], off
	s_mov_b32 m0, s0
	v_readfirstlane_b32 s0, v117
	v_lshl_add_u64 v[94:95], v[94:95], 0, v[92:93]
	global_load_lds_dwordx4 v[106:107], off
	s_mov_b32 m0, s0
	v_readfirstlane_b32 s0, v118
	global_load_lds_dwordx4 v[94:95], off
	s_mov_b32 m0, s0
	s_nop 0
	global_load_lds_dwordx4 v[104:105], off
	s_branch .LBB0_996

.LBB0_1057:
	s_and_b32 s1, s0, 7
	s_mul_i32 s1, s1, s2
	s_ashr_i32 s0, s0, 3
	s_add_i32 s0, s1, s0
	s_ashr_i32 s1, s0, 31
	s_lshr_b32 s1, s1, 26
	s_add_i32 s1, s0, s1
	s_and_b32 s19, s1, 0xffffffc0
	s_sub_i32 s0, s0, s19
	s_lshl_b32 s1, s1, 4
	s_lshl_b32 s19, s0, 7
	s_and_b32 s1, s1, 0xfffffc00
	s_and_b32 s19, s19, 0x380
	s_lshl_b32 s0, s0, 4
	s_waitcnt vmcnt(0)
	s_and_b32 s38, s0, 0xffffff80
	s_or_b32 s19, s1, s19
	v_mov_b32_e32 v2, 0
	s_ashr_i32 s39, s38, 31
	v_mad_i64_i32 v[66:67], s[0:1], s19, v208, v[82:83]
	v_mad_i64_i32 v[68:69], s[0:1], s19, v208, v[84:85]
	v_mad_i64_i32 v[100:101], s[0:1], s19, v208, v[86:87]
	v_mad_i64_i32 v[102:103], s[0:1], s19, v208, v[88:89]
	v_mad_i64_i32 v[104:105], s[0:1], s38, v208, v[90:91]
	v_mad_i64_i32 v[106:107], s[0:1], s38, v208, v[92:93]
	v_mad_i64_i32 v[108:109], s[0:1], s38, v208, v[94:95]
	v_mad_i64_i32 v[110:111], s[0:1], s38, v208, v[96:97]
	s_mov_b32 s22, 0
	v_mov_b32_e32 v3, v2
	v_mov_b32_e32 v4, v2
	v_mov_b32_e32 v5, v2
	v_mov_b32_e32 v6, v2
	v_mov_b32_e32 v7, v2
	v_mov_b32_e32 v8, v2
	v_mov_b32_e32 v9, v2
	v_mov_b32_e32 v10, v2
	v_mov_b32_e32 v11, v2
	v_mov_b32_e32 v12, v2
	v_mov_b32_e32 v13, v2
	v_mov_b32_e32 v14, v2
	v_mov_b32_e32 v15, v2
	v_mov_b32_e32 v16, v2
	v_mov_b32_e32 v17, v2
	v_mov_b32_e32 v18, v2
	v_mov_b32_e32 v19, v2
	v_mov_b32_e32 v20, v2
	v_mov_b32_e32 v21, v2
	v_mov_b32_e32 v22, v2
	v_mov_b32_e32 v23, v2
	v_mov_b32_e32 v24, v2
	v_mov_b32_e32 v25, v2
	v_mov_b32_e32 v26, v2
	v_mov_b32_e32 v27, v2
	v_mov_b32_e32 v28, v2
	v_mov_b32_e32 v29, v2
	v_mov_b32_e32 v30, v2
	v_mov_b32_e32 v31, v2
	v_mov_b32_e32 v32, v2
	v_mov_b32_e32 v33, v2
	v_mov_b32_e32 v34, v2
	v_mov_b32_e32 v35, v2
	v_mov_b32_e32 v36, v2
	v_mov_b32_e32 v37, v2
	v_mov_b32_e32 v38, v2
	v_mov_b32_e32 v39, v2
	v_mov_b32_e32 v40, v2
	v_mov_b32_e32 v41, v2
	v_mov_b32_e32 v42, v2
	v_mov_b32_e32 v43, v2
	v_mov_b32_e32 v44, v2
	v_mov_b32_e32 v45, v2
	v_mov_b32_e32 v46, v2
	v_mov_b32_e32 v47, v2
	v_mov_b32_e32 v48, v2
	v_mov_b32_e32 v49, v2
	v_mov_b32_e32 v50, v2
	v_mov_b32_e32 v51, v2
	v_mov_b32_e32 v52, v2
	v_mov_b32_e32 v53, v2
	v_mov_b32_e32 v54, v2
	v_mov_b32_e32 v55, v2
	v_mov_b32_e32 v56, v2
	v_mov_b32_e32 v57, v2
	v_mov_b32_e32 v58, v2
	v_mov_b32_e32 v59, v2
	v_mov_b32_e32 v60, v2
	v_mov_b32_e32 v61, v2
	v_mov_b32_e32 v62, v2
	v_mov_b32_e32 v63, v2
	v_mov_b32_e32 v64, v2
	v_mov_b32_e32 v65, v2
	s_mov_b32 s24, s25
	v_and_b32_e32 v214, 63, v188
	v_lshrrev_b32_e32 v215, 3, v214
	v_and_b32_e32 v216, 7, v214
	v_xor_b32_e32 v216, v216, v215
	v_mul_u32_u24_e32 v246, 0x1600, v215
	v_lshl_add_u32 v246, v216, 4, v246
	v_add_u32_e32 v247, 0xb000, v246
	v_add_u32_e32 v248, 0x16000, v246
	v_add_u32_e32 v249, 0x21000, v246
	v_lshrrev_b32_e32 v250, 6, v188
	v_lshlrev_b32_e32 v250, 12, v250
	v_readfirstlane_b32 s98, v66
	v_readfirstlane_b32 s99, v67
	v_readfirstlane_b32 s100, v104
	v_readfirstlane_b32 s101, v105
	s_add_u32 s98, s98, s42
	s_addc_u32 s99, s99, s43
	s_add_u32 s100, s100, s42
	s_addc_u32 s101, s101, s43
	s_waitcnt vmcnt(0) lgkmcnt(0)
	s_barrier
.LBB0_1058:
	s_and_b32 s0, s22, 0x2000
	s_xor_b32 s1, s0, 0x2000
	s_lshl_b32 s0, s0, 1
	v_add_u32_e32 v99, s0, v125
	v_add_u32_e32 v162, s0, v126
	v_add_u32_e32 v142, v99, v128
	v_add_u32_e32 v158, v162, v128
	ds_read_b128 v[130:133], v142
	ds_read_b128 v[134:137], v142 offset:2048
	ds_read_b128 v[138:141], v142 offset:4096
	ds_read_b128 v[142:145], v142 offset:6144
	ds_read_b128 v[146:149], v158 offset:32768
	ds_read_b128 v[150:153], v158 offset:34816
	ds_read_b128 v[154:157], v158 offset:36864
	ds_read_b128 v[158:161], v158 offset:38912
	s_lshl_b32 s1, s1, 1
	v_readfirstlane_b32 s0, v250
	v_add_u32_e32 v99, v99, v129
	s_add_u32 m0, s0, s1
	ds_read_b128 v[214:217], v99
	global_load_lds_dwordx4 v246, s[98:99]
	s_add_u32 m0, m0, 0x8000
	ds_read_b128 v[218:221], v99 offset:2048
	global_load_lds_dwordx4 v246, s[100:101]
	s_add_u32 m0, m0, 0xffff8400
	ds_read_b128 v[222:225], v99 offset:4096
	global_load_lds_dwordx4 v247, s[98:99]
	s_add_u32 m0, m0, 0x8000
	ds_read_b128 v[226:229], v99 offset:6144
	global_load_lds_dwordx4 v247, s[100:101]
	s_add_u32 m0, m0, 0xffff8400
	v_add_u32_e32 v99, v162, v129
	ds_read_b128 v[230:233], v99 offset:32768
	global_load_lds_dwordx4 v248, s[98:99]
	s_add_u32 m0, m0, 0x8000
	ds_read_b128 v[234:237], v99 offset:34816
	global_load_lds_dwordx4 v248, s[100:101]
	s_add_u32 m0, m0, 0xffff8400
	ds_read_b128 v[238:241], v99 offset:36864
	global_load_lds_dwordx4 v249, s[98:99]
	s_add_u32 m0, m0, 0x8000
	s_setprio 1
	s_waitcnt lgkmcnt(7)
	ds_read_b128 v[242:245], v99 offset:38912
	global_load_lds_dwordx4 v249, s[100:101]
	s_add_u32 s98, s98, 0x80
	s_addc_u32 s99, s99, 0
	s_add_u32 s100, s100, 0x80
	s_addc_u32 s101, s101, 0
	v_mfma_f32_16x16x32_bf16 v[2:5], v[146:149], v[130:133], v[2:5]
	v_mfma_f32_16x16x32_bf16 v[6:9], v[150:153], v[130:133], v[6:9]
	v_mfma_f32_16x16x32_bf16 v[10:13], v[154:157], v[130:133], v[10:13]
	v_mfma_f32_16x16x32_bf16 v[14:17], v[158:161], v[130:133], v[14:17]
	v_mfma_f32_16x16x32_bf16 v[18:21], v[146:149], v[134:137], v[18:21]
	v_mfma_f32_16x16x32_bf16 v[22:25], v[150:153], v[134:137], v[22:25]
	v_mfma_f32_16x16x32_bf16 v[26:29], v[154:157], v[134:137], v[26:29]
	v_mfma_f32_16x16x32_bf16 v[30:33], v[158:161], v[134:137], v[30:33]
	v_mfma_f32_16x16x32_bf16 v[34:37], v[146:149], v[138:141], v[34:37]
	v_mfma_f32_16x16x32_bf16 v[38:41], v[150:153], v[138:141], v[38:41]
	v_mfma_f32_16x16x32_bf16 v[42:45], v[154:157], v[138:141], v[42:45]
	v_mfma_f32_16x16x32_bf16 v[46:49], v[158:161], v[138:141], v[46:49]
	v_mfma_f32_16x16x32_bf16 v[50:53], v[146:149], v[142:145], v[50:53]
	v_mfma_f32_16x16x32_bf16 v[54:57], v[150:153], v[142:145], v[54:57]
	v_mfma_f32_16x16x32_bf16 v[58:61], v[154:157], v[142:145], v[58:61]
	v_mfma_f32_16x16x32_bf16 v[62:65], v[158:161], v[142:145], v[62:65]
	s_waitcnt lgkmcnt(0)
	v_mfma_f32_16x16x32_bf16 v[2:5], v[230:233], v[214:217], v[2:5]
	v_mfma_f32_16x16x32_bf16 v[6:9], v[234:237], v[214:217], v[6:9]
	v_mfma_f32_16x16x32_bf16 v[10:13], v[238:241], v[214:217], v[10:13]
	v_mfma_f32_16x16x32_bf16 v[14:17], v[242:245], v[214:217], v[14:17]
	v_mfma_f32_16x16x32_bf16 v[18:21], v[230:233], v[218:221], v[18:21]
	v_mfma_f32_16x16x32_bf16 v[22:25], v[234:237], v[218:221], v[22:25]
	v_mfma_f32_16x16x32_bf16 v[26:29], v[238:241], v[218:221], v[26:29]
	v_mfma_f32_16x16x32_bf16 v[30:33], v[242:245], v[218:221], v[30:33]
	v_mfma_f32_16x16x32_bf16 v[34:37], v[230:233], v[222:225], v[34:37]
	v_mfma_f32_16x16x32_bf16 v[38:41], v[234:237], v[222:225], v[38:41]
	v_mfma_f32_16x16x32_bf16 v[42:45], v[238:241], v[222:225], v[42:45]
	v_mfma_f32_16x16x32_bf16 v[46:49], v[242:245], v[222:225], v[46:49]
	v_mfma_f32_16x16x32_bf16 v[50:53], v[230:233], v[226:229], v[50:53]
	v_mfma_f32_16x16x32_bf16 v[54:57], v[234:237], v[226:229], v[54:57]
	v_mfma_f32_16x16x32_bf16 v[58:61], v[238:241], v[226:229], v[58:61]
	v_mfma_f32_16x16x32_bf16 v[62:65], v[242:245], v[226:229], v[62:65]
	s_setprio 0
	s_waitcnt vmcnt(0)
	s_add_u32 s42, s42, 0x80
	s_addc_u32 s43, s43, 0
	s_addk_i32 s22, 0x2000
	s_cmpk_eq_i32 s42, 0x1580
	s_waitcnt vmcnt(0)
	s_barrier
	s_cbranch_scc0 .LBB0_1058
	s_andn2_b64 vcc, exec, s[40:41]
	s_cbranch_vccnz .LBB0_1054
	v_lshl_add_u64 v[66:67], s[44:45], 1, v[78:79]
	v_readfirstlane_b32 s0, v113
	v_lshl_add_u64 v[68:69], v[66:67], 0, v[70:71]
	v_lshl_add_u64 v[104:105], s[46:47], 1, v[80:81]
	s_mov_b32 m0, s0
	v_readfirstlane_b32 s0, v114
	v_lshl_add_u64 v[106:107], v[104:105], 0, v[76:77]
	v_lshl_add_u64 v[108:109], v[104:105], 0, v[74:75]
	v_lshl_add_u64 v[110:111], v[104:105], 0, v[72:73]
	v_lshl_add_u64 v[104:105], v[104:105], 0, v[70:71]
	global_load_lds_dwordx4 v[68:69], off
	s_mov_b32 m0, s0
	v_readfirstlane_b32 s0, v115
	v_lshl_add_u64 v[100:101], v[66:67], 0, v[72:73]
	global_load_lds_dwordx4 v[104:105], off
	s_mov_b32 m0, s0
	v_readfirstlane_b32 s0, v116
	global_load_lds_dwordx4 v[100:101], off
	s_mov_b32 m0, s0
	v_readfirstlane_b32 s0, v117
	v_lshl_add_u64 v[102:103], v[66:67], 0, v[74:75]
	global_load_lds_dwordx4 v[110:111], off
	s_mov_b32 m0, s0
	v_readfirstlane_b32 s0, v118
	global_load_lds_dwordx4 v[102:103], off
	s_mov_b32 m0, s0
	v_readfirstlane_b32 s0, v119
	v_lshl_add_u64 v[66:67], v[66:67], 0, v[76:77]
	global_load_lds_dwordx4 v[108:109], off
	s_mov_b32 m0, s0
	v_readfirstlane_b32 s0, v120
	global_load_lds_dwordx4 v[66:67], off
	s_mov_b32 m0, s0
	s_nop 0
	global_load_lds_dwordx4 v[106:107], off
	s_branch .LBB0_1054

	.amdhsa_kernel _Z6k_mega6Params
		.amdhsa_group_segment_fixed_size 0
		.amdhsa_private_segment_fixed_size 0
		.amdhsa_kernarg_size 496
		.amdhsa_user_sgpr_count 2
		.amdhsa_user_sgpr_dispatch_ptr 0
		.amdhsa_user_sgpr_queue_ptr 0
		.amdhsa_user_sgpr_kernarg_segment_ptr 1
		.amdhsa_user_sgpr_dispatch_id 0
		.amdhsa_user_sgpr_kernarg_preload_length 0
		.amdhsa_user_sgpr_kernarg_preload_offset 0
		.amdhsa_user_sgpr_private_segment_size 0
		.amdhsa_uses_dynamic_stack 0
		.amdhsa_enable_private_segment 0
		.amdhsa_system_sgpr_workgroup_id_x 1
		.amdhsa_system_sgpr_workgroup_id_y 0
		.amdhsa_system_sgpr_workgroup_id_z 0
		.amdhsa_system_sgpr_workgroup_info 0
		.amdhsa_system_vgpr_workitem_id 2
		.amdhsa_next_free_vgpr 256
		.amdhsa_next_free_sgpr 102
		.amdhsa_accum_offset 256
		.amdhsa_reserve_vcc 1
		.amdhsa_float_round_mode_32 0
		.amdhsa_float_round_mode_16_64 0
		.amdhsa_float_denorm_mode_32 3
		.amdhsa_float_denorm_mode_16_64 3
		.amdhsa_dx10_clamp 1
		.amdhsa_ieee_mode 1
		.amdhsa_fp16_overflow 0
		.amdhsa_tg_split 0
		.amdhsa_exception_fp_ieee_invalid_op 0
		.amdhsa_exception_fp_denorm_src 0
		.amdhsa_exception_fp_ieee_div_zero 0
		.amdhsa_exception_fp_ieee_overflow 0
		.amdhsa_exception_fp_ieee_underflow 0
		.amdhsa_exception_fp_ieee_inexact 0
		.amdhsa_exception_int_div_zero 0
	.end_amdhsa_kernel

.Lfunc_end0:
	.size	_Z6k_mega6Params, .Lfunc_end0-_Z6k_mega6Params
	.set _Z6k_mega6Params.num_vgpr, 256
	.set _Z6k_mega6Params.num_agpr, 0
	.set _Z6k_mega6Params.numbered_sgpr, 102
	.set _Z6k_mega6Params.num_named_barrier, 0
	.set _Z6k_mega6Params.private_seg_size, 0
	.set _Z6k_mega6Params.uses_vcc, 1
	.set _Z6k_mega6Params.uses_flat_scratch, 0
	.set _Z6k_mega6Params.has_dyn_sized_stack, 0
	.set _Z6k_mega6Params.has_recursion, 0
	.set _Z6k_mega6Params.has_indirect_call, 0

amdhsa.kernels:
  - .agpr_count:     0
    .args:
      - .offset:         0
        .size:           240
        .value_kind:     by_value
      - .offset:         240
        .size:           4
        .value_kind:     hidden_block_count_x
      - .offset:         244
        .size:           4
        .value_kind:     hidden_block_count_y
      - .offset:         248
        .size:           4
        .value_kind:     hidden_block_count_z
      - .offset:         252
        .size:           2
        .value_kind:     hidden_group_size_x
      - .offset:         254
        .size:           2
        .value_kind:     hidden_group_size_y
      - .offset:         256
        .size:           2
        .value_kind:     hidden_group_size_z
      - .offset:         258
        .size:           2
        .value_kind:     hidden_remainder_x
      - .offset:         260
        .size:           2
        .value_kind:     hidden_remainder_y
      - .offset:         262
        .size:           2
        .value_kind:     hidden_remainder_z
      - .offset:         280
        .size:           8
        .value_kind:     hidden_global_offset_x
      - .offset:         288
        .size:           8
        .value_kind:     hidden_global_offset_y
      - .offset:         296
        .size:           8
        .value_kind:     hidden_global_offset_z
      - .offset:         304
        .size:           2
        .value_kind:     hidden_grid_dims
      - .offset:         328
        .size:           8
        .value_kind:     hidden_multigrid_sync_arg
      - .offset:         360
        .size:           4
        .value_kind:     hidden_dynamic_lds_size
    .group_segment_fixed_size: 0
    .kernarg_segment_align: 8
    .kernarg_segment_size: 496
    .language:       OpenCL C
    .language_version:
      - 2
      - 0
    .max_flat_workgroup_size: 256
    .name:           _Z6k_mega6Params
    .private_segment_fixed_size: 0
    .sgpr_count:     108
    .sgpr_spill_count: 249
    .symbol:         _Z6k_mega6Params.kd
    .uniform_work_group_size: 1
    .uses_dynamic_stack: false
    .vgpr_count:     256
    .vgpr_spill_count: 0
    .wavefront_size: 64
